# attention softmax row sums: two add-zero instructions removed (bit-identical), on top of v70
# speedup vs baseline: 1.0081x; 1.0081x over previous
; DEV unsigned cvt_pk_bf16(float lo, float hi) { unsigned r; asm volatile("v_cvt_pk_bf16_f32 %0, %1, %2" : "=v"(r) : "v"(lo), "v"(hi)); return r; }
; DEV void attn_tile(LAS unsigned char* lds, const bf16x8 (&qf)[2][2], int tl, int kpos0, int mode, bool near, bool rowsel, const float (&cbias)[2],
;                    unsigned kb, unsigned vb_, unsigned btb, int g4, float (&mrun)[2], float (&lrun)[2], f32x4 (&O)[2][4]) {
;     ...
;         float rs = 0.f;
; #pragma unroll
;         for (int kt = 0; kt < 4; ++kt)
; #pragma unroll
;             for (int r = 0; r < 4; ++r) { const float p = __builtin_amdgcn_exp2f(sc[hh][kt][r]); sc[hh][kt][r] = p; rs += p; }
;         lrun[hh] += rs;
; #pragma unroll
;         for (int kc = 0; kc < 2; ++kc) { u32x4 w; w.x = cvt_pk_bf16(sc[hh][2 * kc][0], sc[hh][2 * kc][1]); w.y = cvt_pk_bf16(sc[hh][2 * kc][2], sc[hh][2 * kc][3]);
;             w.z = cvt_pk_bf16(sc[hh][2 * kc + 1][0], sc[hh][2 * kc + 1][1]); w.w = cvt_pk_bf16(sc[hh][2 * kc + 1][2], sc[hh][2 * kc + 1][3]); pf[hh][kc] = as_bf16x8(w); }
.Lst_y_entry:
	v_exp_f32_e32 v92, v92
	v_exp_f32_e32 v93, v93
	v_exp_f32_e32 v94, v94
	v_exp_f32_e32 v95, v95
	v_exp_f32_e32 v88, v88
	v_exp_f32_e32 v89, v89
	v_exp_f32_e32 v90, v90
	v_exp_f32_e32 v91, v91
	v_exp_f32_e32 v153, v84
	v_exp_f32_e32 v154, v85
	v_exp_f32_e32 v155, v86
	v_exp_f32_e32 v156, v87
	v_exp_f32_e32 v157, v80
	v_exp_f32_e32 v158, v81
	v_exp_f32_e32 v159, v82
	v_exp_f32_e32 v160, v83
	v_cvt_pk_bf16_f32 v162, v92, v93
	v_cvt_pk_bf16_f32 v163, v94, v95
	v_cvt_pk_bf16_f32 v164, v88, v89
	v_cvt_pk_bf16_f32 v165, v90, v91
	v_cvt_pk_bf16_f32 v166, v153, v154
	v_cvt_pk_bf16_f32 v167, v155, v156
	v_cvt_pk_bf16_f32 v168, v157, v158
	v_cvt_pk_bf16_f32 v169, v159, v160
	v_add_f32_e32 v92, v93, v92
	v_add_f32_e32 v92, v94, v92
	v_add_f32_e32 v92, v95, v92
	v_add_f32_e32 v88, v88, v92
	v_add_f32_e32 v88, v89, v88
	v_add_f32_e32 v88, v90, v88
	v_add_f32_e32 v88, v91, v88
	v_add_f32_e32 v88, v153, v88
	v_add_f32_e32 v88, v154, v88
	v_add_f32_e32 v88, v155, v88
	v_add_f32_e32 v88, v156, v88
	v_add_f32_e32 v88, v157, v88
	v_exp_f32_e32 v76, v76
	v_add_f32_e32 v88, v158, v88
	v_exp_f32_e32 v77, v77
	v_add_f32_e32 v88, v159, v88
	v_exp_f32_e32 v78, v78
	v_add_f32_e32 v88, v160, v88
	v_exp_f32_e32 v79, v79
	v_add_f32_e32 v151, v151, v88
	v_exp_f32_e32 v72, v72
	v_add_f32_e32 v88, v77, v76
	v_exp_f32_e32 v73, v73
	v_add_f32_e32 v88, v78, v88
	v_exp_f32_e32 v74, v74
	v_add_f32_e32 v88, v79, v88
	v_exp_f32_e32 v75, v75
	v_add_f32_e32 v88, v72, v88
	v_exp_f32_e32 v64, v64
	v_add_f32_e32 v88, v73, v88
	v_exp_f32_e32 v65, v65
	v_add_f32_e32 v88, v74, v88
	v_exp_f32_e32 v66, v66
	v_add_f32_e32 v88, v75, v88
	v_exp_f32_e32 v67, v67
	v_add_f32_e32 v88, v64, v88
	v_exp_f32_e32 v89, v68
	v_add_f32_e32 v88, v65, v88
	v_add_f32_e32 v88, v66, v88
	v_add_f32_e32 v88, v67, v88
	v_add_f32_e32 v68, v89, v88
	v_exp_f32_e32 v88, v69
	v_exp_f32_e32 v90, v70
	v_exp_f32_e32 v91, v71
	v_add_f32_e32 v68, v88, v68
	v_add_f32_e32 v68, v90, v68
	v_add_f32_e32 v68, v91, v68
	v_add_f32_e32 v148, v148, v68
	v_cvt_pk_bf16_f32 v68, v76, v77
	v_cvt_pk_bf16_f32 v69, v78, v79
	v_cvt_pk_bf16_f32 v70, v72, v73
	v_cvt_pk_bf16_f32 v71, v74, v75
	v_cvt_pk_bf16_f32 v64, v64, v65
	v_cvt_pk_bf16_f32 v65, v66, v67
	v_cvt_pk_bf16_f32 v66, v89, v88
	v_cvt_pk_bf16_f32 v67, v90, v91
	s_cmp_eq_u32 s100, 1
	s_cbranch_scc0 .Lst_nokpre
	v_add_u32_e32 v228, s98, v141
	ds_read_b128 v[72:75], v228
	ds_read_b128 v[76:79], v228 offset:64
	ds_read_b128 v[80:83], v228 offset:2304
	ds_read_b128 v[84:87], v228 offset:2368
	ds_read_b128 v[88:91], v228 offset:4608
	ds_read_b128 v[154:157], v228 offset:4672
	ds_read_b128 v[92:95], v228 offset:6912
	ds_read_b128 v[158:161], v228 offset:6976
